# diff attention: LDS-DMA K/V staging (K x2, V x3 buffers) + waves 4-7 defer each tile's PV block to the next iteration (de-phased SIMD partners)
# baseline (speedup 1.0000x reference)
.LBB0_356:
	s_or_b64 exec, exec, s[0:1]
	v_readlane_b32 s0, v255, 49
	v_readlane_b32 s1, v255, 50
	v_ashrrev_i32_e32 v5, 6, v2
	v_lshl_add_u32 v2, v2, 2, 0
	v_lshlrev_b32_e32 v6, 5, v5
	v_and_b32_e32 v4, 63, v0
	v_add_u32_e32 v2, 0x20100, v2
	global_load_dword v177, v1, s[0:1]
	s_lshl_b32 s0, s16, 9
	v_lshl_add_u32 v7, s19, 8, v6
	s_and_b32 s4, s0, 0x3000
	s_waitcnt vmcnt(1)
	ds_write_b32 v2, v3
	v_add_u32_e32 v179, s4, v7
	v_lshlrev_b32_e32 v2, 13, v5
	v_lshlrev_b32_e32 v3, 2, v4
	v_and_or_b32 v8, v0, 31, v179
	v_add3_u32 v228, 0, v2, v3
	s_mov_b32 s98, 0x4800
	s_cmp_eq_u32 s83, 0x1c0
	s_cselect_b32 s98, 0x5800, s98
	v_add_u32_e32 v228, s98, v228
	v_mov_b64_e32 v[2:3], s[88:89]
	s_lshl_b32 s21, s19, 2
	v_mad_i64_i32 v[2:3], s[0:1], v8, s87, v[2:3]
	s_add_i32 s22, s21, 4
	s_lshl_b32 s20, s18, 7
	s_lshl_b32 s94, s18, 8
	s_mul_i32 s0, s4, 0x9000
	s_add_u32 s0, s88, s0
	s_addc_u32 s1, s89, 0
	s_add_u32 s23, s0, s94
	s_addc_u32 s24, s1, 0
	s_lshl_b32 s0, s18, 22
	v_readlane_b32 s1, v255, 47
	s_add_u32 s0, s1, s0
	v_readlane_b32 s1, v255, 48
	s_addc_u32 s1, s1, 0
	s_lshl_b32 s4, s4, 1
	v_lshrrev_b32_e32 v0, 1, v0
	s_add_u32 s6, s0, s4
	v_lshl_add_u64 v[2:3], v[2:3], 0, s[94:95]
	v_and_b32_e32 v0, 16, v0
	s_addc_u32 s7, s1, 0
	s_lshl_b32 s0, s17, 8
	v_lshl_add_u64 v[166:167], v[2:3], 0, v[0:1]
	v_subrev_u32_e32 v0, s0, v6
	v_or_b32_e32 v229, 31, v7
	s_or_b32 s25, s21, 2
	v_add_u32_e32 v230, 0xe41, v0
	s_mov_b64 s[0:1], 0
	s_mov_b64 s[8:9], -1
	s_branch .LBB0_358

.LBB0_358:
	s_lshl_b64 s[0:1], s[0:1], 1
	v_lshl_add_u64 v[2:3], v[166:167], 0, s[0:1]
	global_load_dwordx4 v[98:101], v[2:3], off
	global_load_dwordx4 v[102:105], v[2:3], off offset:32
	global_load_dwordx4 v[106:109], v[2:3], off offset:64
	global_load_dwordx4 v[110:113], v[2:3], off offset:96
	v_mbcnt_lo_u32_b32 v28, -1, 0
	v_mbcnt_hi_u32_b32 v28, -1, v28
	s_xor_b64 s[8:9], s[8:9], -1
	v_add_u32_e32 v12, s83, v28
	v_ashrrev_i32_e32 v0, 31, v12
	v_lshrrev_b32_e32 v0, 29, v0
	v_add_u32_e32 v0, v12, v0
	v_ashrrev_i32_e32 v231, 3, v0
	v_and_b32_e32 v0, -8, v0
	v_sub_u32_e32 v29, v12, v0
	v_lshlrev_b32_e32 v2, 3, v29
	v_ashrrev_i32_e32 v16, 3, v12
	v_add_u32_e32 v12, 0x200, v12
	s_add_u32 s0, s23, s0
	v_ashrrev_i32_e32 v3, 31, v2
	v_lshlrev_b32_e32 v0, 4, v28
	v_ashrrev_i32_e32 v20, 3, v12
	s_addc_u32 s1, s24, s1
	v_lshlrev_b64 v[2:3], 1, v[2:3]
	v_and_b32_e32 v0, 0x70, v0
	v_ashrrev_i32_e32 v17, 31, v16
	v_ashrrev_i32_e32 v21, 31, v20
	v_lshl_add_u64 v[168:169], s[0:1], 0, v[2:3]
	v_lshl_add_u64 v[170:171], s[6:7], 0, v[0:1]
	v_lshlrev_b64 v[172:173], 15, v[16:17]
	v_lshlrev_b64 v[174:175], 15, v[20:21]
	s_mov_b32 s98, 0x1c71c71d
	s_add_i32 s99, s83, 0
	v_add_u32_e32 v4, s99, v28
	v_add_u32_e32 v5, 0xfffffdc0, v4
	v_cmp_gt_u32_e32 vcc, 0x240, v4
	v_mov_b32_e32 v9, 0x8000
	v_mov_b32_e32 v10, 0x9000
	v_cndmask_b32_e32 v6, v5, v4, vcc
	v_mul_hi_u32 v7, v6, s98
	v_mul_u32_u24_e32 v8, 9, v7
	v_sub_u32_e32 v8, v6, v8
	v_min_u32_e32 v8, 7, v8
	v_lshlrev_b32_e32 v12, 4, v8
	v_mov_b32_e32 v14, 0x800
	v_cndmask_b32_e32 v14, 0, v14, vcc
	v_add_u32_e32 v12, v12, v14
	v_mov_b32_e32 v13, 0
	v_cndmask_b32_e32 v9, v9, v10, vcc
	v_mad_u64_u32 v[10:11], s[100:101], v7, v9, v[12:13]
	v_lshl_add_u64 v[4:5], s[0:1], 0, v[10:11]
	v_lshl_add_u64 v[6:7], s[6:7], 0, v[10:11]
	v_cndmask_b32_e32 v114, v6, v4, vcc
	v_cndmask_b32_e32 v115, v7, v5, vcc
	v_mov_b32_e32 v9, 0x80
	v_mov_b32_e32 v10, 0x240000
	v_cndmask_b32_e32 v122, v9, v10, vcc
	s_add_i32 s99, s83, 512
	v_add_u32_e32 v4, s99, v28
	v_add_u32_e32 v5, 0xfffffdc0, v4
	v_cmp_gt_u32_e32 vcc, 0x240, v4
	v_mov_b32_e32 v9, 0x8000
	v_mov_b32_e32 v10, 0x9000
	v_cndmask_b32_e32 v6, v5, v4, vcc
	v_mul_hi_u32 v7, v6, s98
	v_mul_u32_u24_e32 v8, 9, v7
	v_sub_u32_e32 v8, v6, v8
	v_min_u32_e32 v8, 7, v8
	v_lshlrev_b32_e32 v12, 4, v8
	v_mov_b32_e32 v14, 0x800
	v_cndmask_b32_e32 v14, 0, v14, vcc
	v_add_u32_e32 v12, v12, v14
	v_mov_b32_e32 v13, 0
	v_cndmask_b32_e32 v9, v9, v10, vcc
	v_mad_u64_u32 v[10:11], s[100:101], v7, v9, v[12:13]
	v_lshl_add_u64 v[4:5], s[0:1], 0, v[10:11]
	v_lshl_add_u64 v[6:7], s[6:7], 0, v[10:11]
	v_cndmask_b32_e32 v116, v6, v4, vcc
	v_cndmask_b32_e32 v117, v7, v5, vcc
	v_mov_b32_e32 v9, 0x80
	v_mov_b32_e32 v10, 0x240000
	v_cndmask_b32_e32 v123, v9, v10, vcc
	s_add_i32 s99, s83, 1024
	v_add_u32_e32 v4, s99, v28
	v_add_u32_e32 v5, 0xfffffdc0, v4
	v_cmp_gt_u32_e32 vcc, 0x240, v4
	v_mov_b32_e32 v9, 0x8000
	v_mov_b32_e32 v10, 0x9000
	v_cndmask_b32_e32 v6, v5, v4, vcc
	v_mul_hi_u32 v7, v6, s98
	v_mul_u32_u24_e32 v8, 9, v7
	v_sub_u32_e32 v8, v6, v8
	v_min_u32_e32 v8, 7, v8
	v_lshlrev_b32_e32 v12, 4, v8
	v_mov_b32_e32 v14, 0x800
	v_cndmask_b32_e32 v14, 0, v14, vcc
	v_add_u32_e32 v12, v12, v14
	v_mov_b32_e32 v13, 0
	v_cndmask_b32_e32 v9, v9, v10, vcc
	v_mad_u64_u32 v[10:11], s[100:101], v7, v9, v[12:13]
	v_lshl_add_u64 v[4:5], s[0:1], 0, v[10:11]
	v_lshl_add_u64 v[6:7], s[6:7], 0, v[10:11]
	v_cndmask_b32_e32 v118, v6, v4, vcc
	v_cndmask_b32_e32 v119, v7, v5, vcc
	v_mov_b32_e32 v9, 0x80
	v_mov_b32_e32 v10, 0x240000
	v_cndmask_b32_e32 v124, v9, v10, vcc
	s_add_i32 s99, s83, 1536
	v_add_u32_e32 v4, s99, v28
	v_add_u32_e32 v5, 0xfffffdc0, v4
	v_cmp_gt_u32_e32 vcc, 0x240, v4
	v_mov_b32_e32 v9, 0x8000
	v_mov_b32_e32 v10, 0x9000
	v_cndmask_b32_e32 v6, v5, v4, vcc
	v_mul_hi_u32 v7, v6, s98
	v_mul_u32_u24_e32 v8, 9, v7
	v_sub_u32_e32 v8, v6, v8
	v_min_u32_e32 v8, 7, v8
	v_lshlrev_b32_e32 v12, 4, v8
	v_mov_b32_e32 v14, 0x800
	v_cndmask_b32_e32 v14, 0, v14, vcc
	v_add_u32_e32 v12, v12, v14
	v_mov_b32_e32 v13, 0
	v_cndmask_b32_e32 v9, v9, v10, vcc
	v_mad_u64_u32 v[10:11], s[100:101], v7, v9, v[12:13]
	v_lshl_add_u64 v[4:5], s[0:1], 0, v[10:11]
	v_lshl_add_u64 v[6:7], s[6:7], 0, v[10:11]
	v_cndmask_b32_e32 v120, v6, v4, vcc
	v_cndmask_b32_e32 v121, v7, v5, vcc
	v_mov_b32_e32 v9, 0x80
	v_mov_b32_e32 v10, 0x240000
	v_cndmask_b32_e32 v125, v9, v10, vcc
	s_mov_b32 s100, 0
	s_bitcmp1_b32 s100, 0
	s_cselect_b32 s98, 0x2400, 0
	s_lshl_b32 m0, s83, 4
	s_add_i32 s98, s98, m0
	s_add_i32 s99, m0, 0x4400
	v_mad_u64_u32 v[204:205], vcc, v122, s100, v[114:115]
	s_mov_b32 m0, s98
	v_mad_u64_u32 v[206:207], vcc, v123, s100, v[116:117]
	global_load_lds_dwordx4 v[204:205], off
	s_add_i32 m0, s98, 0x2000
	s_cmp_eq_u32 s83, 0
	s_cselect_b32 m0, m0, s99
	v_mad_u64_u32 v[208:209], vcc, v124, s100, v[118:119]
	global_load_lds_dwordx4 v[206:207], off
	s_add_i32 m0, s99, 0x2000
	s_cmp_ge_u32 s83, 0xc0
	global_load_lds_dwordx4 v[208:209], off
	s_cbranch_scc1 .Ldma_p0
	v_mad_u64_u32 v[210:211], vcc, v125, s100, v[120:121]
	s_add_i32 m0, s99, 0x4000
	s_nop 0
	global_load_lds_dwordx4 v[210:211], off
.Ldma_p0:
	v_add_u32_e32 v17, 64, v231
	v_mad_i64_i32 v[4:5], s[4:5], v231, s87, v[168:169]
	v_lshl_add_u64 v[18:19], v[170:171], 0, v[172:173]
	v_lshl_add_u64 v[22:23], v[170:171], 0, v[174:175]
	v_mad_i64_i32 v[24:25], s[4:5], v17, s87, v[168:169]
	v_add_u32_e32 v17, 0x80, v231
	s_nop 0
	v_mad_i64_i32 v[26:27], s[4:5], v17, s87, v[168:169]
	v_add_u32_e32 v17, 0xc0, v231
	v_mov_b64_e32 v[18:19], s[0:1]
	v_mad_i64_i32 v[18:19], s[0:1], v17, s87, v[18:19]
	v_lshl_add_u64 v[2:3], v[18:19], 0, v[2:3]
	v_lshl_add_u64 v[18:19], s[6:7], 0, v[172:173]
	v_lshl_add_u64 v[18:19], v[18:19], 0, v[0:1]
	v_lshl_add_u64 v[22:23], s[6:7], 0, v[174:175]
	v_lshl_add_u64 v[22:23], v[22:23], 0, v[0:1]
	v_lshlrev_b32_e32 v18, 1, v28
	v_lshrrev_b32_e32 v19, 1, v28
	v_and_b32_e32 v22, 19, v28
	v_and_b32_e32 v18, 8, v18
	v_and_b32_e32 v19, 4, v19
	v_add_u32_e32 v234, 0, v0
	v_or3_b32 v0, v18, v22, v19
	v_mul_lo_u32 v237, v20, s86
	v_mul_lo_u32 v19, v231, s86
	v_lshlrev_b32_e32 v20, 4, v29
	v_mov_b32_e32 v17, s77
	v_mul_lo_u32 v235, v16, s86
	v_add3_u32 v239, 0, v19, v20
	v_bfe_u32 v23, v28, 5, 1
	v_add_u32_e32 v16, v234, v235
	v_add_u32_e32 v18, v234, v237
	v_and_b32_e32 v21, 31, v28
	v_lshlrev_b32_e32 v232, 4, v23
	v_lshlrev_b32_e32 v23, 3, v23
	v_mov_b32_e32 v2, v1
	v_mov_b32_e32 v3, v1
	v_mul_u32_u24_e32 v233, 0x90, v21
	v_sub_u32_e32 v236, v21, v23
	v_mul_u32_u24_e32 v238, 0x90, v0
	v_mov_b32_e32 v0, v1
	s_mov_b32 s94, 0
	v_mov_b32_e32 v178, 0
	v_mov_b32_e32 v240, v230
	v_mov_b32_e32 v241, 0
	s_mov_b32 s26, s94
	s_waitcnt vmcnt(0) lgkmcnt(0)
	s_barrier
	ds_read_b32 v176, v17
	v_mov_b32_e32 v14, v1
	v_mov_b32_e32 v15, v1
	v_mov_b32_e32 v4, v1
	v_mov_b32_e32 v5, v1
	v_mov_b32_e32 v6, v1
	v_mov_b32_e32 v7, v1
	v_mov_b32_e32 v8, v1
	v_mov_b32_e32 v9, v1
	v_mov_b32_e32 v10, v1
	v_mov_b32_e32 v11, v1
	v_mov_b32_e32 v12, v1
	v_mov_b32_e32 v13, v1
	v_mov_b64_e32 v[64:65], v[14:15]
	v_mov_b64_e32 v[48:49], v[14:15]
	v_mov_b64_e32 v[32:33], v[14:15]
	v_mov_b64_e32 v[62:63], v[12:13]
	v_mov_b64_e32 v[60:61], v[10:11]
	v_mov_b64_e32 v[58:59], v[8:9]
	v_mov_b64_e32 v[56:57], v[6:7]
	v_mov_b64_e32 v[54:55], v[4:5]
	v_mov_b64_e32 v[52:53], v[2:3]
	v_mov_b64_e32 v[50:51], v[0:1]
	v_mov_b64_e32 v[46:47], v[12:13]
	v_mov_b64_e32 v[44:45], v[10:11]
	v_mov_b64_e32 v[42:43], v[8:9]
	v_mov_b64_e32 v[40:41], v[6:7]
	v_mov_b64_e32 v[38:39], v[4:5]
	v_mov_b64_e32 v[36:37], v[2:3]
	v_mov_b64_e32 v[34:35], v[0:1]
	v_mov_b64_e32 v[30:31], v[12:13]
	v_mov_b64_e32 v[28:29], v[10:11]
	v_mov_b64_e32 v[26:27], v[8:9]
	v_mov_b64_e32 v[24:25], v[6:7]
	v_mov_b64_e32 v[22:23], v[4:5]
	v_mov_b64_e32 v[20:21], v[2:3]
	v_mov_b64_e32 v[18:19], v[0:1]
	v_mov_b64_e32 v[16:17], v[14:15]
	v_mov_b64_e32 v[14:15], v[12:13]
	v_mov_b64_e32 v[12:13], v[10:11]
	v_mov_b64_e32 v[10:11], v[8:9]
	v_mov_b64_e32 v[8:9], v[6:7]
	v_mov_b64_e32 v[6:7], v[4:5]
	v_mov_b64_e32 v[4:5], v[2:3]
	v_mov_b64_e32 v[2:3], v[0:1]
	s_mov_b32 s101, 0
.LBB0_359:
	s_and_b32 s100, s101, 3
	s_cmp_eq_u32 s100, 3
	s_cbranch_scc1 .Ldf_p3
.Ldf_after1:
	s_add_i32 s27, s26, 1
	s_cmp_lt_u32 s27, s22
	s_cselect_b64 s[10:11], -1, 0
	s_cmp_ge_u32 s27, s22
	s_cbranch_scc1 .LBB0_362
	s_bitcmp1_b32 s27, 0
	s_cselect_b32 s98, 0x2400, 0
	s_lshl_b32 m0, s83, 4
	s_add_i32 s98, s98, m0
	s_add_i32 s99, m0, 0x8c00
	v_mad_u64_u32 v[204:205], vcc, v122, s27, v[114:115]
	s_mov_b32 m0, s98
	v_mad_u64_u32 v[206:207], vcc, v123, s27, v[116:117]
	global_load_lds_dwordx4 v[204:205], off
	s_add_i32 m0, s98, 0x2000
	s_cmp_eq_u32 s83, 0
	s_cselect_b32 m0, m0, s99
	v_mad_u64_u32 v[208:209], vcc, v124, s27, v[118:119]
	global_load_lds_dwordx4 v[206:207], off
	s_add_i32 m0, s99, 0x2000
	s_cmp_ge_u32 s83, 0xc0
	global_load_lds_dwordx4 v[208:209], off
	s_cbranch_scc1 .LBB0_362
	v_mad_u64_u32 v[210:211], vcc, v125, s27, v[120:121]
	s_add_i32 m0, s99, 0x4000
	s_nop 0
	global_load_lds_dwordx4 v[210:211], off
.LBB0_362:
	v_cmp_le_i32_e32 vcc, s94, v229
	s_and_saveexec_b64 s[12:13], vcc
	s_cbranch_execz .LBB0_372
	s_bitcmp1_b32 s26, 0
	s_cselect_b32 s0, 0x2400, 0
	s_add_i32 s0, s0, 0
	v_add_u32_e32 v0, s0, v232
	v_add_u32_e32 v180, v0, v238
	ds_read_b128 v[66:69], v180
	ds_read_b128 v[150:153], v180 offset:32
	ds_read_b128 v[70:73], v180 offset:4608
	ds_read_b128 v[154:157], v180 offset:4640
	s_waitcnt lgkmcnt(3)
	v_mfma_f32_32x32x16_bf16 v[82:97], v[66:69], v[98:101], 0
	s_waitcnt lgkmcnt(1)
	v_mfma_f32_32x32x16_bf16 v[66:81], v[70:73], v[98:101], 0
	v_mfma_f32_32x32x16_bf16 v[82:97], v[150:153], v[102:105], v[82:97]
	ds_read_b128 v[150:153], v180 offset:64
	ds_read_b128 v[158:161], v180 offset:96
	ds_read_b128 v[162:165], v180 offset:4672
	ds_read_b128 v[180:183], v180 offset:4704
	s_waitcnt lgkmcnt(4)
	v_mfma_f32_32x32x16_bf16 v[66:81], v[154:157], v[102:105], v[66:81]
	s_waitcnt lgkmcnt(3)
	v_mfma_f32_32x32x16_bf16 v[82:97], v[150:153], v[106:109], v[82:97]
	s_mov_b32 s99, 0x2400
	v_add3_u32 v242, v232, v233, s99
	s_waitcnt lgkmcnt(1)
	v_mfma_f32_32x32x16_bf16 v[66:81], v[162:165], v[106:109], v[66:81]
	v_mfma_f32_32x32x16_bf16 v[82:97], v[158:161], v[110:113], v[82:97]
	ds_read_b128 v[162:165], v242 offset:9216
	ds_read_b128 v[158:161], v242 offset:13824
	ds_read_b128 v[154:157], v242 offset:18432
	ds_read_b128 v[150:153], v242 offset:23040
	s_waitcnt lgkmcnt(4)
	v_mfma_f32_32x32x16_bf16 v[66:81], v[180:183], v[110:113], v[66:81]
	s_movk_i32 s0, 0xbf
	v_add_u32_e32 v180, 0x80, v240
	v_add3_u32 v0, v236, v240, s0
	v_cmp_gt_i32_e32 vcc, s85, v180
	s_and_saveexec_b64 s[0:1], vcc
	s_xor_b64 s[0:1], exec, s[0:1]
	s_cbranch_execz .LBB0_365
	v_add_u32_e32 v181, -1, v0
	v_add_u32_e32 v182, 0x1fe, v0
	v_add_u32_e32 v183, 0x1fd, v0
	v_add_u32_e32 v184, 0x1fc, v0
	v_add_u32_e32 v185, 0x1fb, v0
	v_add_u32_e32 v186, 0x1fa, v0
	v_add_u32_e32 v187, 0x1f9, v0
	v_and_b32_e32 v180, 0x1ff, v0
	s_add_i32 s4, 0, 0x20100
	v_and_b32_e32 v181, 0x1ff, v181
	v_and_b32_e32 v182, 0x1ff, v182
	v_and_b32_e32 v183, 0x1ff, v183
	v_and_b32_e32 v184, 0x1ff, v184
	v_and_b32_e32 v185, 0x1ff, v185
	v_and_b32_e32 v186, 0x1ff, v186
	v_and_b32_e32 v187, 0x1ff, v187
	v_lshl_add_u32 v180, v180, 2, s4
	v_lshl_add_u32 v181, v181, 2, s4
	v_lshl_add_u32 v182, v182, 2, s4
	v_lshl_add_u32 v183, v183, 2, s4
	v_lshl_add_u32 v184, v184, 2, s4
	v_lshl_add_u32 v185, v185, 2, s4
	v_lshl_add_u32 v186, v186, 2, s4
	v_lshl_add_u32 v187, v187, 2, s4
	ds_read_b32 v180, v180
	ds_read_b32 v181, v181
	ds_read_b32 v182, v182
	ds_read_b32 v183, v183
	ds_read_b32 v184, v184
	ds_read_b32 v185, v185
	ds_read_b32 v186, v186
	ds_read_b32 v187, v187
	s_waitcnt lgkmcnt(6)
	v_pk_add_f32 v[180:181], v[180:181], v[178:179] op_sel_hi:[1,0] neg_lo:[0,1] neg_hi:[0,1]
	s_nop 0
	v_pk_fma_f32 v[180:181], v[82:83], s[82:83], v[180:181] op_sel_hi:[1,0,1]
	s_waitcnt lgkmcnt(4)
	v_pk_add_f32 v[82:83], v[182:183], v[178:179] op_sel_hi:[1,0] neg_lo:[0,1] neg_hi:[0,1]
	v_max3_f32 v188, v180, s33, v181
	v_pk_fma_f32 v[182:183], v[84:85], s[82:83], v[82:83] op_sel_hi:[1,0,1]
	s_waitcnt lgkmcnt(2)
	v_pk_add_f32 v[82:83], v[184:185], v[178:179] op_sel_hi:[1,0] neg_lo:[0,1] neg_hi:[0,1]
	v_max3_f32 v84, v188, v182, v183
	v_pk_fma_f32 v[184:185], v[86:87], s[82:83], v[82:83] op_sel_hi:[1,0,1]
	s_waitcnt lgkmcnt(0)
	v_pk_add_f32 v[82:83], v[186:187], v[178:179] op_sel_hi:[1,0] neg_lo:[0,1] neg_hi:[0,1]
	v_max3_f32 v84, v84, v184, v185
	v_pk_fma_f32 v[186:187], v[88:89], s[82:83], v[82:83] op_sel_hi:[1,0,1]
	v_add_u32_e32 v82, 0x1f0, v0
	v_max3_f32 v188, v84, v186, v187
	v_add_u32_e32 v83, 0x1ef, v0
	v_add_u32_e32 v84, 0x1ee, v0
	v_add_u32_e32 v85, 0x1ed, v0
	v_add_u32_e32 v86, 0x1ec, v0
	v_add_u32_e32 v87, 0x1eb, v0
	v_add_u32_e32 v88, 0x1ea, v0
	v_add_u32_e32 v89, 0x1e9, v0
	v_and_b32_e32 v82, 0x1ff, v82
	v_and_b32_e32 v83, 0x1ff, v83
	v_and_b32_e32 v84, 0x1ff, v84
	v_and_b32_e32 v85, 0x1ff, v85
	v_and_b32_e32 v86, 0x1ff, v86
	v_and_b32_e32 v87, 0x1ff, v87
	v_and_b32_e32 v88, 0x1ff, v88
	v_and_b32_e32 v89, 0x1ff, v89
	v_lshl_add_u32 v82, v82, 2, s4
	v_lshl_add_u32 v83, v83, 2, s4
	v_lshl_add_u32 v84, v84, 2, s4
	v_lshl_add_u32 v85, v85, 2, s4
	v_lshl_add_u32 v86, v86, 2, s4
	v_lshl_add_u32 v87, v87, 2, s4
	v_lshl_add_u32 v88, v88, 2, s4
	v_lshl_add_u32 v89, v89, 2, s4
	ds_read_b32 v82, v82
	ds_read_b32 v83, v83
	ds_read_b32 v84, v84
	ds_read_b32 v85, v85
	ds_read_b32 v86, v86
	ds_read_b32 v87, v87
	ds_read_b32 v88, v88
	ds_read_b32 v89, v89
	s_waitcnt lgkmcnt(6)
	v_pk_add_f32 v[82:83], v[82:83], v[178:179] op_sel_hi:[1,0] neg_lo:[0,1] neg_hi:[0,1]
	s_nop 0
	v_pk_fma_f32 v[192:193], v[90:91], s[82:83], v[82:83] op_sel_hi:[1,0,1]
	s_waitcnt lgkmcnt(4)
	v_pk_add_f32 v[82:83], v[84:85], v[178:179] op_sel_hi:[1,0] neg_lo:[0,1] neg_hi:[0,1]
	v_max3_f32 v90, v188, v192, v193
	v_pk_fma_f32 v[206:207], v[92:93], s[82:83], v[82:83] op_sel_hi:[1,0,1]
	s_waitcnt lgkmcnt(2)
	v_pk_add_f32 v[82:83], v[86:87], v[178:179] op_sel_hi:[1,0] neg_lo:[0,1] neg_hi:[0,1]
	v_max3_f32 v84, v90, v206, v207
	v_pk_fma_f32 v[188:189], v[94:95], s[82:83], v[82:83] op_sel_hi:[1,0,1]
	s_waitcnt lgkmcnt(0)
	v_pk_add_f32 v[82:83], v[88:89], v[178:179] op_sel_hi:[1,0] neg_lo:[0,1] neg_hi:[0,1]
	v_max3_f32 v84, v84, v188, v189
	v_pk_fma_f32 v[190:191], v[96:97], s[82:83], v[82:83] op_sel_hi:[1,0,1]
	v_add_u32_e32 v82, 0x1e0, v0
	v_max3_f32 v90, v84, v190, v191
	v_add_u32_e32 v83, 0x1df, v0
	v_add_u32_e32 v84, 0x1de, v0
	v_add_u32_e32 v85, 0x1dd, v0
	v_add_u32_e32 v86, 0x1dc, v0
	v_add_u32_e32 v87, 0x1db, v0
	v_add_u32_e32 v88, 0x1da, v0
	v_add_u32_e32 v89, 0x1d9, v0
	v_and_b32_e32 v82, 0x1ff, v82
	v_and_b32_e32 v83, 0x1ff, v83
	v_and_b32_e32 v84, 0x1ff, v84
	v_and_b32_e32 v85, 0x1ff, v85
	v_and_b32_e32 v86, 0x1ff, v86
	v_and_b32_e32 v87, 0x1ff, v87
	v_and_b32_e32 v88, 0x1ff, v88
	v_and_b32_e32 v89, 0x1ff, v89
	v_lshl_add_u32 v82, v82, 2, s4
	v_lshl_add_u32 v83, v83, 2, s4
	v_lshl_add_u32 v84, v84, 2, s4
	v_lshl_add_u32 v85, v85, 2, s4
	v_lshl_add_u32 v86, v86, 2, s4
	v_lshl_add_u32 v87, v87, 2, s4
	v_lshl_add_u32 v88, v88, 2, s4
	v_lshl_add_u32 v89, v89, 2, s4
	ds_read_b32 v82, v82
	ds_read_b32 v83, v83
	ds_read_b32 v84, v84
	ds_read_b32 v85, v85
	ds_read_b32 v86, v86
	ds_read_b32 v87, v87
	ds_read_b32 v88, v88
	ds_read_b32 v89, v89
	s_waitcnt lgkmcnt(6)
	v_pk_add_f32 v[82:83], v[82:83], v[178:179] op_sel_hi:[1,0] neg_lo:[0,1] neg_hi:[0,1]
	s_nop 0
	v_pk_fma_f32 v[204:205], v[66:67], s[82:83], v[82:83] op_sel_hi:[1,0,1]
	s_waitcnt lgkmcnt(4)
	v_pk_add_f32 v[66:67], v[84:85], v[178:179] op_sel_hi:[1,0] neg_lo:[0,1] neg_hi:[0,1]
	v_max3_f32 v82, v90, v204, v205
	v_pk_fma_f32 v[208:209], v[68:69], s[82:83], v[66:67] op_sel_hi:[1,0,1]
	s_waitcnt lgkmcnt(2)
	v_pk_add_f32 v[66:67], v[86:87], v[178:179] op_sel_hi:[1,0] neg_lo:[0,1] neg_hi:[0,1]
	v_max3_f32 v68, v82, v208, v209
	v_pk_fma_f32 v[210:211], v[70:71], s[82:83], v[66:67] op_sel_hi:[1,0,1]
	s_waitcnt lgkmcnt(0)
	v_pk_add_f32 v[66:67], v[88:89], v[178:179] op_sel_hi:[1,0] neg_lo:[0,1] neg_hi:[0,1]
	v_max3_f32 v68, v68, v210, v211
	v_pk_fma_f32 v[212:213], v[72:73], s[82:83], v[66:67] op_sel_hi:[1,0,1]
	v_add_u32_e32 v66, 0x1d0, v0
	v_max3_f32 v82, v68, v212, v213
	v_add_u32_e32 v67, 0x1cf, v0
	v_add_u32_e32 v68, 0x1ce, v0
	v_add_u32_e32 v69, 0x1cd, v0
	v_add_u32_e32 v70, 0x1cc, v0
	v_add_u32_e32 v71, 0x1cb, v0
	v_add_u32_e32 v72, 0x1ca, v0
	v_and_b32_e32 v66, 0x1ff, v66
	v_and_b32_e32 v67, 0x1ff, v67
	v_and_b32_e32 v68, 0x1ff, v68
	v_and_b32_e32 v69, 0x1ff, v69
	v_and_b32_e32 v70, 0x1ff, v70
	v_and_b32_e32 v71, 0x1ff, v71
	v_and_b32_e32 v72, 0x1ff, v72
	v_add_u32_e32 v0, 0x1c9, v0
	v_lshl_add_u32 v66, v66, 2, s4
	v_lshl_add_u32 v67, v67, 2, s4
	v_lshl_add_u32 v68, v68, 2, s4
	v_lshl_add_u32 v69, v69, 2, s4
	v_lshl_add_u32 v70, v70, 2, s4
	v_lshl_add_u32 v71, v71, 2, s4
	v_lshl_add_u32 v72, v72, 2, s4
	v_and_b32_e32 v0, 0x1ff, v0
	v_lshl_add_u32 v0, v0, 2, s4
	ds_read_b32 v66, v66
	ds_read_b32 v67, v67
	ds_read_b32 v68, v68
	ds_read_b32 v69, v69
	ds_read_b32 v70, v70
	ds_read_b32 v71, v71
	ds_read_b32 v72, v72
	ds_read_b32 v73, v0
	s_waitcnt lgkmcnt(6)
	v_pk_add_f32 v[66:67], v[66:67], v[178:179] op_sel_hi:[1,0] neg_lo:[0,1] neg_hi:[0,1]
	s_nop 0
	v_pk_fma_f32 v[214:215], v[74:75], s[82:83], v[66:67] op_sel_hi:[1,0,1]
	s_waitcnt lgkmcnt(4)
	v_pk_add_f32 v[66:67], v[68:69], v[178:179] op_sel_hi:[1,0] neg_lo:[0,1] neg_hi:[0,1]
	v_max3_f32 v0, v82, v214, v215
	v_pk_fma_f32 v[216:217], v[76:77], s[82:83], v[66:67] op_sel_hi:[1,0,1]
	s_waitcnt lgkmcnt(2)
	v_pk_add_f32 v[66:67], v[70:71], v[178:179] op_sel_hi:[1,0] neg_lo:[0,1] neg_hi:[0,1]
	v_max3_f32 v0, v0, v216, v217
	v_pk_fma_f32 v[218:219], v[78:79], s[82:83], v[66:67] op_sel_hi:[1,0,1]
	s_waitcnt lgkmcnt(0)
	v_pk_add_f32 v[66:67], v[72:73], v[178:179] op_sel_hi:[1,0] neg_lo:[0,1] neg_hi:[0,1]
	v_max3_f32 v0, v0, v218, v219
	v_pk_fma_f32 v[220:221], v[80:81], s[82:83], v[66:67] op_sel_hi:[1,0,1]
	s_nop 0
	v_max3_f32 v243, v0, v220, v221

.LBB0_371:
	s_cmp_ge_u32 s83, 0x100
	s_cbranch_scc0 .Ldf_p1
	s_or_b32 s101, s101, 1
	s_branch .LBB0_372
.Ldf_p1:
	v_exp_f32_e32 v66, v180
	v_exp_f32_e32 v67, v181
	v_exp_f32_e32 v68, v182
	v_exp_f32_e32 v69, v183
	v_exp_f32_e32 v70, v184
	v_exp_f32_e32 v71, v185
	v_exp_f32_e32 v72, v186
	v_exp_f32_e32 v73, v187
	v_cvt_pk_bf16_f32 v74, v66, v67
	v_cvt_pk_bf16_f32 v75, v68, v69
	v_cvt_pk_bf16_f32 v76, v70, v71
	v_cvt_pk_bf16_f32 v77, v72, v73
	ds_read_b128 v[82:85], v242 offset:9248
	v_exp_f32_e32 v78, v188
	s_waitcnt lgkmcnt(4)
	v_mfma_f32_32x32x16_bf16 v[50:65], v[162:165], v[74:77], v[50:65]
	v_exp_f32_e32 v79, v189
	v_exp_f32_e32 v80, v190
	v_exp_f32_e32 v81, v191
	v_exp_f32_e32 v162, v218
	v_cvt_pk_bf16_f32 v88, v78, v79
	v_exp_f32_e32 v163, v219
	v_cvt_pk_bf16_f32 v89, v80, v81
	s_waitcnt lgkmcnt(3)
	v_mfma_f32_32x32x16_bf16 v[34:49], v[158:161], v[74:77], v[34:49]
	v_exp_f32_e32 v158, v214
	v_exp_f32_e32 v159, v215
	v_exp_f32_e32 v160, v216
	v_exp_f32_e32 v161, v217
	v_exp_f32_e32 v164, v220
	v_exp_f32_e32 v165, v221
	v_pk_add_f32 v[66:67], v[66:67], 0 op_sel_hi:[1,0]
	s_waitcnt lgkmcnt(2)
	v_mfma_f32_32x32x16_bf16 v[18:33], v[154:157], v[74:77], v[18:33]
	v_exp_f32_e32 v154, v210
	v_exp_f32_e32 v155, v211
	v_exp_f32_e32 v156, v212
	v_exp_f32_e32 v157, v213
	v_pk_add_f32 v[66:67], v[68:69], v[66:67]
	s_nop 0
	v_pk_add_f32 v[66:67], v[70:71], v[66:67]
	s_waitcnt lgkmcnt(1)
	v_mfma_f32_32x32x16_bf16 v[2:17], v[150:153], v[74:77], v[2:17]
	v_exp_f32_e32 v74, v192
	v_exp_f32_e32 v75, v193
	v_exp_f32_e32 v76, v206
	v_exp_f32_e32 v77, v207
	v_exp_f32_e32 v150, v204
	v_cvt_pk_bf16_f32 v86, v74, v75
	v_exp_f32_e32 v151, v205
	v_cvt_pk_bf16_f32 v87, v76, v77
	v_exp_f32_e32 v152, v208
	v_exp_f32_e32 v153, v209
	s_waitcnt lgkmcnt(0)
	v_mfma_f32_32x32x16_bf16 v[50:65], v[82:85], v[86:89], v[50:65]
	ds_read_b128 v[82:85], v242 offset:13856
	v_add_f32_e64 v66, v72, v66
	v_add_f32_e64 v67, v73, v67
	v_add_f32_e64 v66, v74, v66
	v_add_f32_e64 v67, v75, v67
	v_pk_add_f32 v[66:67], v[76:77], v[66:67]
	s_waitcnt lgkmcnt(0)
	v_mfma_f32_32x32x16_bf16 v[34:49], v[82:85], v[86:89], v[34:49]
	ds_read_b128 v[82:85], v242 offset:18464
	v_add_f32_e64 v66, v78, v66
	v_add_f32_e64 v67, v79, v67
	v_add_f32_e64 v66, v80, v66
	v_add_f32_e64 v67, v81, v67
	v_pk_add_f32 v[66:67], v[150:151], v[66:67]
	s_waitcnt lgkmcnt(0)
	v_mfma_f32_32x32x16_bf16 v[18:33], v[82:85], v[86:89], v[18:33]
	ds_read_b128 v[82:85], v242 offset:23072
	ds_read_b128 v[90:93], v242 offset:9280
	v_add_f32_e64 v66, v152, v66
	v_add_f32_e64 v67, v153, v67
	v_add_f32_e64 v66, v154, v66
	v_add_f32_e64 v67, v155, v67
	v_pk_add_f32 v[66:67], v[156:157], v[66:67]
	s_waitcnt lgkmcnt(1)
	v_mfma_f32_32x32x16_bf16 v[2:17], v[82:85], v[86:89], v[2:17]
	ds_read_b128 v[86:89], v242 offset:13888
	v_cvt_pk_bf16_f32 v82, v150, v151
	v_cvt_pk_bf16_f32 v83, v152, v153
	v_cvt_pk_bf16_f32 v84, v154, v155
	v_cvt_pk_bf16_f32 v85, v156, v157
	v_pk_add_f32 v[66:67], v[158:159], v[66:67]
	s_waitcnt lgkmcnt(0)
	v_mfma_f32_32x32x16_bf16 v[34:49], v[86:89], v[82:85], v[34:49]
	ds_read_b128 v[86:89], v242 offset:18496
	v_add_f32_e64 v66, v160, v66
	v_add_f32_e64 v67, v161, v67
	v_add_f32_e64 v66, v162, v66
	v_add_f32_e64 v67, v163, v67
	v_pk_add_f32 v[66:67], v[164:165], v[66:67]
	v_mfma_f32_32x32x16_bf16 v[50:65], v[90:93], v[82:85], v[50:65]
	v_add_f32_e32 v66, v66, v67
	v_fmac_f32_e32 v66, v241, v0
	s_waitcnt lgkmcnt(0)
	v_mfma_f32_32x32x16_bf16 v[18:33], v[86:89], v[82:85], v[18:33]
	ds_read_b128 v[86:89], v242 offset:23104
	ds_read_b128 v[90:93], v242 offset:9312
	s_waitcnt lgkmcnt(1)
	v_mfma_f32_32x32x16_bf16 v[2:17], v[86:89], v[82:85], v[2:17]
	v_cvt_pk_bf16_f32 v82, v158, v159
	v_cvt_pk_bf16_f32 v83, v160, v161
	v_cvt_pk_bf16_f32 v84, v162, v163
	v_cvt_pk_bf16_f32 v85, v164, v165
	s_waitcnt lgkmcnt(0)
	s_nop 0
	v_mfma_f32_32x32x16_bf16 v[50:65], v[90:93], v[82:85], v[50:65]
	ds_read_b128 v[86:89], v242 offset:13920
	ds_read_b128 v[90:93], v242 offset:18528
	ds_read_b128 v[94:97], v242 offset:23136
	s_waitcnt lgkmcnt(2)
	v_mfma_f32_32x32x16_bf16 v[34:49], v[86:89], v[82:85], v[34:49]
	s_waitcnt lgkmcnt(1)
	v_mfma_f32_32x32x16_bf16 v[18:33], v[90:93], v[82:85], v[18:33]
	s_waitcnt lgkmcnt(0)
	v_mfma_f32_32x32x16_bf16 v[2:17], v[94:97], v[82:85], v[2:17]
	v_mov_b32_e32 v241, v66
	s_cmp_ge_u32 s83, 0x100
	s_cbranch_scc1 .Ldf_ret1

.Ldf_ret1:
	s_andn2_b32 s101, s101, 3
	s_bitcmp1_b32 s101, 2
	s_cbranch_scc1 .Ldf_exit_resume
	s_branch .Ldf_after2

.LBB0_375:
	s_and_b32 s100, s101, 3
	s_cmp_eq_u32 s100, 1
	s_cbranch_scc1 .Ldf_p1
.Ldf_after2:
	s_cmp_ge_u32 s26, s25
	s_cbranch_scc1 .LBB0_378
	s_add_i32 s100, s26, 2
	s_bitcmp1_b32 s100, 0
	s_cselect_b32 s98, 0x2400, 0
	s_lshl_b32 m0, s83, 4
	s_add_i32 s98, s98, m0
	s_add_i32 s99, m0, 0xd400
	v_mad_u64_u32 v[204:205], vcc, v122, s100, v[114:115]
	s_mov_b32 m0, s98
	v_mad_u64_u32 v[206:207], vcc, v123, s100, v[116:117]
	global_load_lds_dwordx4 v[204:205], off
	s_add_i32 m0, s98, 0x2000
	s_cmp_eq_u32 s83, 0
	s_cselect_b32 m0, m0, s99
	v_mad_u64_u32 v[208:209], vcc, v124, s100, v[118:119]
	global_load_lds_dwordx4 v[206:207], off
	s_add_i32 m0, s99, 0x2000
	s_cmp_ge_u32 s83, 0xc0
	global_load_lds_dwordx4 v[208:209], off
	s_cbranch_scc1 .LBB0_378
	v_mad_u64_u32 v[210:211], vcc, v125, s100, v[120:121]
	s_add_i32 m0, s99, 0x4000
	s_nop 0
	global_load_lds_dwordx4 v[210:211], off
.LBB0_378:
	s_add_i32 s0, s94, 64
	v_cmp_le_i32_e32 vcc, s0, v229
	s_and_saveexec_b64 s[10:11], vcc
	s_cbranch_execz .LBB0_387
	s_bitcmp1_b32 s27, 0
	s_cselect_b32 s0, 0x2400, 0
	s_add_i32 s0, s0, 0
	v_add_u32_e32 v0, s0, v232
	v_add_u32_e32 v180, v0, v238
	ds_read_b128 v[66:69], v180
	ds_read_b128 v[150:153], v180 offset:32
	ds_read_b128 v[70:73], v180 offset:4608
	ds_read_b128 v[154:157], v180 offset:4640
	s_waitcnt lgkmcnt(3)
	v_mfma_f32_32x32x16_bf16 v[82:97], v[66:69], v[98:101], 0
	s_waitcnt lgkmcnt(1)
	v_mfma_f32_32x32x16_bf16 v[66:81], v[70:73], v[98:101], 0
	v_mfma_f32_32x32x16_bf16 v[82:97], v[150:153], v[102:105], v[82:97]
	ds_read_b128 v[150:153], v180 offset:64
	ds_read_b128 v[158:161], v180 offset:96
	ds_read_b128 v[162:165], v180 offset:4672
	ds_read_b128 v[180:183], v180 offset:4704
	s_waitcnt lgkmcnt(4)
	v_mfma_f32_32x32x16_bf16 v[66:81], v[154:157], v[102:105], v[66:81]
	s_waitcnt lgkmcnt(3)
	v_mfma_f32_32x32x16_bf16 v[82:97], v[150:153], v[106:109], v[82:97]
	s_mov_b32 s99, 0x6c00
	v_add3_u32 v242, v232, v233, s99
	s_waitcnt lgkmcnt(1)
	v_mfma_f32_32x32x16_bf16 v[66:81], v[162:165], v[106:109], v[66:81]
	v_mfma_f32_32x32x16_bf16 v[82:97], v[158:161], v[110:113], v[82:97]
	ds_read_b128 v[162:165], v242 offset:9216
	ds_read_b128 v[158:161], v242 offset:13824
	ds_read_b128 v[154:157], v242 offset:18432
	ds_read_b128 v[150:153], v242 offset:23040
	s_waitcnt lgkmcnt(4)
	v_mfma_f32_32x32x16_bf16 v[66:81], v[180:183], v[110:113], v[66:81]
	s_movk_i32 s0, 0x7f
	v_add_u32_e32 v180, 64, v240
	v_add3_u32 v0, v236, v240, s0
	v_cmp_gt_i32_e32 vcc, s85, v180
	s_and_saveexec_b64 s[0:1], vcc
	s_xor_b64 s[0:1], exec, s[0:1]
	s_cbranch_execnz .LBB0_383
	s_andn2_saveexec_b64 s[0:1], s[0:1]
	s_cbranch_execnz .LBB0_384

.LBB0_386:
	s_cmp_ge_u32 s83, 0x100
	s_cbranch_scc0 .Ldf_p2
	s_or_b32 s101, s101, 2
	s_branch .LBB0_387

.LBB0_388:
	s_and_b32 s100, s101, 3
	s_cmp_eq_u32 s100, 2
	s_cbranch_scc1 .Ldf_p2
.Ldf_after3:
	s_cmp_ge_u32 s12, s22
	s_cbranch_scc1 .LBB0_391
	s_bitcmp1_b32 s12, 0
	s_cselect_b32 s98, 0x2400, 0
	s_lshl_b32 m0, s83, 4
	s_add_i32 s98, s98, m0
	s_add_i32 s99, m0, 0x4400
	v_mad_u64_u32 v[204:205], vcc, v122, s12, v[114:115]
	s_mov_b32 m0, s98
	v_mad_u64_u32 v[206:207], vcc, v123, s12, v[116:117]
	global_load_lds_dwordx4 v[204:205], off
	s_add_i32 m0, s98, 0x2000
	s_cmp_eq_u32 s83, 0
	s_cselect_b32 m0, m0, s99
	v_mad_u64_u32 v[208:209], vcc, v124, s12, v[118:119]
	global_load_lds_dwordx4 v[206:207], off
	s_add_i32 m0, s99, 0x2000
	s_cmp_ge_u32 s83, 0xc0
	global_load_lds_dwordx4 v[208:209], off
	s_cbranch_scc1 .LBB0_391
	v_mad_u64_u32 v[210:211], vcc, v125, s12, v[120:121]
	s_add_i32 m0, s99, 0x4000
	s_nop 0
	global_load_lds_dwordx4 v[210:211], off
.LBB0_391:
	s_add_i32 s0, s94, 0x80
	v_cmp_le_i32_e32 vcc, s0, v229
	s_and_saveexec_b64 s[10:11], vcc
	s_cbranch_execz .LBB0_400
	s_bitcmp1_b32 s26, 0
	s_cselect_b32 s0, 0x2400, 0
	s_add_i32 s0, s0, 0
	v_add_u32_e32 v0, s0, v232
	v_add_u32_e32 v180, v0, v238
	ds_read_b128 v[66:69], v180
	ds_read_b128 v[150:153], v180 offset:32
	ds_read_b128 v[70:73], v180 offset:4608
	ds_read_b128 v[154:157], v180 offset:4640
	s_waitcnt lgkmcnt(3)
	v_mfma_f32_32x32x16_bf16 v[82:97], v[66:69], v[98:101], 0
	s_waitcnt lgkmcnt(1)
	v_mfma_f32_32x32x16_bf16 v[66:81], v[70:73], v[98:101], 0
	v_mfma_f32_32x32x16_bf16 v[82:97], v[150:153], v[102:105], v[82:97]
	ds_read_b128 v[150:153], v180 offset:64
	ds_read_b128 v[158:161], v180 offset:96
	ds_read_b128 v[162:165], v180 offset:4672
	ds_read_b128 v[180:183], v180 offset:4704
	s_waitcnt lgkmcnt(4)
	v_mfma_f32_32x32x16_bf16 v[66:81], v[154:157], v[102:105], v[66:81]
	s_waitcnt lgkmcnt(3)
	v_mfma_f32_32x32x16_bf16 v[82:97], v[150:153], v[106:109], v[82:97]
	s_mov_b32 s99, 0xb400
	v_add3_u32 v242, v232, v233, s99
	s_waitcnt lgkmcnt(1)
	v_mfma_f32_32x32x16_bf16 v[66:81], v[162:165], v[106:109], v[66:81]
	v_mfma_f32_32x32x16_bf16 v[82:97], v[158:161], v[110:113], v[82:97]
	ds_read_b128 v[162:165], v242 offset:9216
	ds_read_b128 v[158:161], v242 offset:13824
	ds_read_b128 v[154:157], v242 offset:18432
	ds_read_b128 v[150:153], v242 offset:23040
	s_waitcnt lgkmcnt(4)
	v_mfma_f32_32x32x16_bf16 v[66:81], v[180:183], v[110:113], v[66:81]
	v_add3_u32 v0, v236, v240, 63
	v_cmp_gt_i32_e32 vcc, s85, v240
	s_and_saveexec_b64 s[0:1], vcc
	s_xor_b64 s[0:1], exec, s[0:1]
	s_cbranch_execnz .LBB0_396
	s_andn2_saveexec_b64 s[0:1], s[0:1]
	s_cbranch_execnz .LBB0_397

.LBB0_399:
	s_cmp_ge_u32 s83, 0x100
	s_cbranch_scc0 .Ldf_p3
	s_or_b32 s101, s101, 3
	s_branch .LBB0_400
.Ldf_p3:
	s_nop 0
	v_exp_f32_e32 v66, v180
	v_exp_f32_e32 v67, v181
	v_exp_f32_e32 v68, v182
	v_exp_f32_e32 v69, v183
	v_exp_f32_e32 v70, v184
	v_exp_f32_e32 v71, v185
	v_exp_f32_e32 v72, v186
	v_exp_f32_e32 v73, v187
	v_cvt_pk_bf16_f32 v74, v66, v67
	v_cvt_pk_bf16_f32 v75, v68, v69
	v_cvt_pk_bf16_f32 v76, v70, v71
	v_cvt_pk_bf16_f32 v77, v72, v73
	ds_read_b128 v[82:85], v242 offset:9248
	v_exp_f32_e32 v78, v188
	s_waitcnt lgkmcnt(4)
	v_mfma_f32_32x32x16_bf16 v[50:65], v[162:165], v[74:77], v[50:65]
	v_exp_f32_e32 v79, v189
	v_exp_f32_e32 v80, v190
	v_exp_f32_e32 v81, v191
	v_exp_f32_e32 v162, v218
	v_cvt_pk_bf16_f32 v88, v78, v79
	v_exp_f32_e32 v163, v219
	v_cvt_pk_bf16_f32 v89, v80, v81
	s_waitcnt lgkmcnt(3)
	v_mfma_f32_32x32x16_bf16 v[34:49], v[158:161], v[74:77], v[34:49]
	v_exp_f32_e32 v158, v214
	v_exp_f32_e32 v159, v215
	v_exp_f32_e32 v160, v216
	v_exp_f32_e32 v161, v217
	v_exp_f32_e32 v164, v220
	v_exp_f32_e32 v165, v221
	v_pk_add_f32 v[66:67], v[66:67], 0 op_sel_hi:[1,0]
	s_waitcnt lgkmcnt(2)
	v_mfma_f32_32x32x16_bf16 v[18:33], v[154:157], v[74:77], v[18:33]
	v_exp_f32_e32 v154, v210
	v_exp_f32_e32 v155, v211
	v_exp_f32_e32 v156, v212
	v_exp_f32_e32 v157, v213
	v_pk_add_f32 v[66:67], v[68:69], v[66:67]
	s_nop 0
	v_pk_add_f32 v[66:67], v[70:71], v[66:67]
	s_waitcnt lgkmcnt(1)
	v_mfma_f32_32x32x16_bf16 v[2:17], v[150:153], v[74:77], v[2:17]
	v_exp_f32_e32 v74, v192
	v_exp_f32_e32 v75, v193
	v_exp_f32_e32 v76, v206
	v_exp_f32_e32 v77, v207
	v_exp_f32_e32 v150, v204
	v_cvt_pk_bf16_f32 v86, v74, v75
	v_exp_f32_e32 v151, v205
	v_cvt_pk_bf16_f32 v87, v76, v77
	v_exp_f32_e32 v152, v208
	v_exp_f32_e32 v153, v209
	s_waitcnt lgkmcnt(0)
	v_mfma_f32_32x32x16_bf16 v[50:65], v[82:85], v[86:89], v[50:65]
	ds_read_b128 v[82:85], v242 offset:13856
	v_add_f32_e64 v66, v72, v66
	v_add_f32_e64 v67, v73, v67
	v_add_f32_e64 v66, v74, v66
	v_add_f32_e64 v67, v75, v67
	v_pk_add_f32 v[66:67], v[76:77], v[66:67]
	s_waitcnt lgkmcnt(0)
	v_mfma_f32_32x32x16_bf16 v[34:49], v[82:85], v[86:89], v[34:49]
	ds_read_b128 v[82:85], v242 offset:18464
	v_add_f32_e64 v66, v78, v66
	v_add_f32_e64 v67, v79, v67
	v_add_f32_e64 v66, v80, v66
	v_add_f32_e64 v67, v81, v67
	v_pk_add_f32 v[66:67], v[150:151], v[66:67]
	s_waitcnt lgkmcnt(0)
	v_mfma_f32_32x32x16_bf16 v[18:33], v[82:85], v[86:89], v[18:33]
	ds_read_b128 v[82:85], v242 offset:23072
	ds_read_b128 v[90:93], v242 offset:9280
	v_add_f32_e64 v66, v152, v66
	v_add_f32_e64 v67, v153, v67
	v_add_f32_e64 v66, v154, v66
	v_add_f32_e64 v67, v155, v67
	v_pk_add_f32 v[66:67], v[156:157], v[66:67]
	s_waitcnt lgkmcnt(1)
	v_mfma_f32_32x32x16_bf16 v[2:17], v[82:85], v[86:89], v[2:17]
	ds_read_b128 v[86:89], v242 offset:13888
	v_cvt_pk_bf16_f32 v82, v150, v151
	v_cvt_pk_bf16_f32 v83, v152, v153
	v_cvt_pk_bf16_f32 v84, v154, v155
	v_cvt_pk_bf16_f32 v85, v156, v157
	v_pk_add_f32 v[66:67], v[158:159], v[66:67]
	s_waitcnt lgkmcnt(0)
	v_mfma_f32_32x32x16_bf16 v[34:49], v[86:89], v[82:85], v[34:49]
	ds_read_b128 v[86:89], v242 offset:18496
	v_add_f32_e64 v66, v160, v66
	v_add_f32_e64 v67, v161, v67
	v_add_f32_e64 v66, v162, v66
	v_add_f32_e64 v67, v163, v67
	v_pk_add_f32 v[66:67], v[164:165], v[66:67]
	v_mfma_f32_32x32x16_bf16 v[50:65], v[90:93], v[82:85], v[50:65]
	v_add_f32_e32 v66, v66, v67
	v_fmac_f32_e32 v66, v241, v0
	s_waitcnt lgkmcnt(0)
	v_mfma_f32_32x32x16_bf16 v[18:33], v[86:89], v[82:85], v[18:33]
	ds_read_b128 v[86:89], v242 offset:23104
	ds_read_b128 v[90:93], v242 offset:9312
	s_waitcnt lgkmcnt(1)
	v_mfma_f32_32x32x16_bf16 v[2:17], v[86:89], v[82:85], v[2:17]
	v_cvt_pk_bf16_f32 v82, v158, v159
	v_cvt_pk_bf16_f32 v83, v160, v161
	v_cvt_pk_bf16_f32 v84, v162, v163
	v_cvt_pk_bf16_f32 v85, v164, v165
	s_waitcnt lgkmcnt(0)
	s_nop 0
	v_mfma_f32_32x32x16_bf16 v[50:65], v[90:93], v[82:85], v[50:65]
	ds_read_b128 v[86:89], v242 offset:13920
	ds_read_b128 v[90:93], v242 offset:18528
	ds_read_b128 v[94:97], v242 offset:23136
	s_waitcnt lgkmcnt(2)
	v_mfma_f32_32x32x16_bf16 v[34:49], v[86:89], v[82:85], v[34:49]
	s_waitcnt lgkmcnt(1)
	v_mfma_f32_32x32x16_bf16 v[18:33], v[90:93], v[82:85], v[18:33]
	s_waitcnt lgkmcnt(0)
	v_mfma_f32_32x32x16_bf16 v[2:17], v[94:97], v[82:85], v[2:17]
	v_mov_b32_e32 v241, v66
	s_cmp_ge_u32 s83, 0x100
	s_cbranch_scc1 .Ldf_ret3

.LBB0_402:
	s_and_b32 s100, s101, 3
	s_cmp_eq_u32 s100, 0
	s_cbranch_scc1 .Ldf_exit_done
	s_or_b32 s101, s101, 4
	s_cmp_eq_u32 s100, 1
	s_cbranch_scc1 .Ldf_p1
	s_cmp_eq_u32 s100, 2
	s_cbranch_scc1 .Ldf_p2
	s_branch .Ldf_p3
.Ldf_exit_resume:
	s_mov_b32 s101, 0
.Ldf_exit_done:
	s_barrier
	v_mov_b32_e32 v0, v241
	v_mov_b32_e32 v66, v241
	s_nop 1
	v_permlane32_swap_b32_e32 v0, v66
	v_cmp_eq_u32_e32 vcc, v0, v241
	s_nop 1
	v_cndmask_b32_e32 v0, v0, v66, vcc
	v_add_f32_e32 v0, v241, v0
	v_div_scale_f32 v66, s[0:1], v0, v0, 1.0
	v_rcp_f32_e32 v67, v66
	s_mov_b64 s[0:1], -1
	v_fma_f32 v68, -v66, v67, 1.0
	v_fmac_f32_e32 v67, v68, v67
	v_div_scale_f32 v68, vcc, 1.0, v0, 1.0
	v_mul_f32_e32 v69, v68, v67
	v_fma_f32 v70, -v66, v69, v68
	v_fmac_f32_e32 v69, v70, v67
	v_fma_f32 v66, -v66, v69, v68
	v_div_fmas_f32 v66, v66, v67, v69
	v_div_fixup_f32 v0, v66, v0, 1.0
	s_and_b64 vcc, exec, s[8:9]
	s_cbranch_vccnz .LBB0_404
	s_andn2_b64 vcc, exec, s[0:1]
	s_cbranch_vccnz .LBB0_357
	s_branch .LBB0_405
